# norm2/norm0 rows: wave64 sum of squares via DPP + permlane16/32 swap (bottom-up tree) instead of 6 serialized ds_bpermute round trips; plus qk-prep DPP
# baseline (speedup 1.0000x reference)
.LBB0_198:
	v_mov_b32_e32 v0, v1
	v_readlane_b32 s22, v255, 2
	v_mbcnt_lo_u32_b32 v0, -1, v0
	v_mbcnt_hi_u32_b32 v0, -1, v0
	v_add_u32_e32 v0, s80, v0
	s_mul_i32 s22, s22, 3
	s_waitcnt lgkmcnt(0)
	v_ashrrev_i32_e32 v2, 6, v0
	v_add_u32_e32 v2, s20, v2
	v_ashrrev_i32_e32 v3, 31, v2
	v_lshl_add_u64 v[4:5], v[2:3], 0, s[94:95]
	v_ashrrev_i32_e32 v6, 12, v2
	v_lshlrev_b32_e32 v0, 2, v0
	v_lshlrev_b64 v[4:5], 12, v[4:5]
	v_add_u32_e32 v6, 1, v6
	v_and_b32_e32 v24, 0xfc, v0
	v_lshl_add_u64 v[4:5], s[64:65], 0, v[4:5]
	v_cndmask_b32_e64 v6, v6, 0, s[12:13]
	v_lshlrev_b32_e32 v0, 2, v24
	v_readlane_b32 s23, v255, 3
	v_add_u32_e32 v6, s22, v6
	v_lshl_add_u64 v[18:19], v[4:5], 0, v[0:1]
	v_mov_b64_e32 v[4:5], s[66:67]
	v_cmp_lt_i32_e32 vcc, v199, v221
	v_mad_i64_i32 v[4:5], s[22:23], v6, s25, v[4:5]
	s_nop 0
	v_cndmask_b32_e32 v6, v220, v199, vcc
	v_cmp_lt_i32_e32 vcc, v200, v221
	v_lshlrev_b32_e32 v54, 2, v6
	s_mov_b64 s[22:23], 0x4b03000
	v_cndmask_b32_e32 v6, v220, v200, vcc
	v_cmp_lt_i32_e32 vcc, v201, v221
	v_lshlrev_b32_e32 v55, 2, v6
	v_lshl_add_u64 v[20:21], v[4:5], 0, s[22:23]
	v_cndmask_b32_e32 v6, v220, v201, vcc
	v_cmp_lt_i32_e32 vcc, v235, v221
	v_lshlrev_b32_e32 v56, 2, v6
	s_mov_b64 s[22:23], 0x4b04000
	v_cndmask_b32_e32 v6, v220, v235, vcc
	v_cmp_lt_i32_e32 vcc, v226, v221
	v_lshlrev_b32_e32 v57, 2, v6
	v_lshlrev_b64 v[2:3], 11, v[2:3]
	v_cndmask_b32_e32 v6, v220, v226, vcc
	v_cmp_lt_i32_e32 vcc, v227, v221
	v_lshl_add_u64 v[38:39], v[4:5], 0, s[22:23]
	v_lshlrev_b32_e32 v58, 2, v6
	v_cndmask_b32_e32 v6, v220, v227, vcc
	v_lshl_add_u64 v[22:23], s[72:73], 0, v[2:3]
	v_lshl_add_u64 v[2:3], v[20:21], 0, v[0:1]
	v_lshl_add_u64 v[14:15], v[38:39], 0, v[0:1]
	v_lshlrev_b32_e32 v59, 2, v6
	v_mov_b32_e32 v60, v2
	v_mov_b32_e32 v61, v3
	v_mov_b32_e32 v62, v14
	v_mov_b32_e32 v63, v15
	global_load_dwordx4 v[66:69], v[18:19], off
	global_load_dwordx4 v[70:73], v[18:19], off offset:1024
	global_load_dwordx4 v[74:77], v[18:19], off offset:2048
	global_load_dwordx4 v[78:81], v[18:19], off offset:3072
	global_load_dwordx4 v[82:85], v0, s[4:5]
	global_load_dwordx4 v[86:89], v0, s[4:5] offset:1024
	global_load_dwordx4 v[90:93], v0, s[4:5] offset:2048
	global_load_dwordx4 v[94:97], v0, s[4:5] offset:3072
	global_load_dwordx4 v[98:101], v[60:61], off
	global_load_dwordx4 v[102:105], v[60:61], off offset:1024
	global_load_dwordx4 v[106:109], v[60:61], off offset:2048
	global_load_dwordx4 v[110:113], v[60:61], off offset:3072
	global_load_dwordx4 v[114:117], v[62:63], off
	global_load_dwordx4 v[118:121], v[62:63], off offset:1024
	global_load_dwordx4 v[122:125], v[62:63], off offset:2048
	global_load_dwordx4 v[126:129], v[62:63], off offset:3072
	v_lshlrev_b32_e32 v14, 1, v24
	v_mov_b32_e32 v15, v1
	v_lshl_add_u64 v[26:27], v[22:23], 0, v[14:15]
	s_add_i32 s21, s21, s81
	s_add_i32 s20, s20, s24
	v_readlane_b32 s22, v255, 2
	v_readlane_b32 s23, v255, 3
	s_cmpk_gt_i32 s21, 0x7ff
	s_waitcnt vmcnt(12)
	v_pk_mul_f32 v[130:131], v[66:67], v[66:67]
	v_pk_fma_f32 v[130:131], v[68:69], v[68:69], v[130:131]
	v_pk_fma_f32 v[130:131], v[70:71], v[70:71], v[130:131]
	v_pk_fma_f32 v[130:131], v[72:73], v[72:73], v[130:131]
	v_pk_fma_f32 v[130:131], v[74:75], v[74:75], v[130:131]
	v_pk_fma_f32 v[130:131], v[76:77], v[76:77], v[130:131]
	v_pk_fma_f32 v[130:131], v[78:79], v[78:79], v[130:131]
	v_pk_fma_f32 v[130:131], v[80:81], v[80:81], v[130:131]
	s_nop 0
	v_add_f32_e32 v44, v130, v131
	s_nop 1
	v_add_f32_dpp v44, v44, v44 quad_perm:[1,0,3,2] row_mask:0xf bank_mask:0xf
	s_nop 1
	v_add_f32_dpp v44, v44, v44 quad_perm:[2,3,0,1] row_mask:0xf bank_mask:0xf
	s_nop 1
	v_add_f32_dpp v44, v44, v44 row_half_mirror row_mask:0xf bank_mask:0xf
	s_nop 1
	v_add_f32_dpp v44, v44, v44 row_mirror row_mask:0xf bank_mask:0xf
	v_mov_b32_e32 v45, v44
	s_nop 1
	v_permlane16_swap_b32_e32 v44, v45
	v_add_f32_e32 v44, v44, v45
	v_mov_b32_e32 v45, v44
	s_nop 1
	v_permlane32_swap_b32_e32 v44, v45
	v_add_f32_e32 v44, v44, v45
	v_fmamk_f32 v44, v44, 0x3a800000, v187
	v_cmp_gt_f32_e32 vcc, s82, v44
	v_mul_f32_e32 v45, 0x4b800000, v44
	s_nop 0
	v_cndmask_b32_e32 v44, v44, v45, vcc
	v_rsq_f32_e32 v44, v44
	s_nop 0
	v_mul_f32_e32 v45, 0x45800000, v44
	v_cndmask_b32_e32 v44, v44, v45, vcc
	s_waitcnt vmcnt(0)
	v_pk_mul_f32 v[66:67], v[66:67], v[44:45] op_sel_hi:[1,0]
	v_pk_mul_f32 v[68:69], v[68:69], v[44:45] op_sel_hi:[1,0]
	v_pk_add_f32 v[114:115], v[114:115], 1.0 op_sel_hi:[1,0]
	v_pk_add_f32 v[116:117], v[116:117], 1.0 op_sel_hi:[1,0]
	v_pk_mul_f32 v[66:67], v[82:83], v[66:67]
	v_pk_mul_f32 v[68:69], v[84:85], v[68:69]
	v_pk_fma_f32 v[98:99], v[114:115], v[66:67], v[98:99]
	v_pk_fma_f32 v[100:101], v[68:69], v[116:117], v[100:101]
	s_nop 0
	v_cvt_pk_bf16_f32 v98, v98, v99
	v_cvt_pk_bf16_f32 v99, v100, v101
	global_store_dwordx2 v[26:27], v[98:99], off
	v_pk_mul_f32 v[70:71], v[70:71], v[44:45] op_sel_hi:[1,0]
	v_pk_mul_f32 v[72:73], v[72:73], v[44:45] op_sel_hi:[1,0]
	v_pk_add_f32 v[118:119], v[118:119], 1.0 op_sel_hi:[1,0]
	v_pk_add_f32 v[120:121], v[120:121], 1.0 op_sel_hi:[1,0]
	v_pk_mul_f32 v[70:71], v[86:87], v[70:71]
	v_pk_mul_f32 v[72:73], v[88:89], v[72:73]
	v_pk_fma_f32 v[102:103], v[118:119], v[70:71], v[102:103]
	v_pk_fma_f32 v[104:105], v[72:73], v[120:121], v[104:105]
	s_nop 0
	v_cvt_pk_bf16_f32 v102, v102, v103
	v_cvt_pk_bf16_f32 v103, v104, v105
	global_store_dwordx2 v[26:27], v[102:103], off offset:512
	v_pk_mul_f32 v[74:75], v[74:75], v[44:45] op_sel_hi:[1,0]
	v_pk_mul_f32 v[76:77], v[76:77], v[44:45] op_sel_hi:[1,0]
	v_pk_add_f32 v[122:123], v[122:123], 1.0 op_sel_hi:[1,0]
	v_pk_add_f32 v[124:125], v[124:125], 1.0 op_sel_hi:[1,0]
	v_pk_mul_f32 v[74:75], v[90:91], v[74:75]
	v_pk_mul_f32 v[76:77], v[92:93], v[76:77]
	v_pk_fma_f32 v[106:107], v[122:123], v[74:75], v[106:107]
	v_pk_fma_f32 v[108:109], v[76:77], v[124:125], v[108:109]
	s_nop 0
	v_cvt_pk_bf16_f32 v106, v106, v107
	v_cvt_pk_bf16_f32 v107, v108, v109
	global_store_dwordx2 v[26:27], v[106:107], off offset:1024
	v_pk_mul_f32 v[78:79], v[78:79], v[44:45] op_sel_hi:[1,0]
	v_pk_mul_f32 v[80:81], v[80:81], v[44:45] op_sel_hi:[1,0]
	v_pk_add_f32 v[126:127], v[126:127], 1.0 op_sel_hi:[1,0]
	v_pk_add_f32 v[128:129], v[128:129], 1.0 op_sel_hi:[1,0]
	v_pk_mul_f32 v[78:79], v[94:95], v[78:79]
	v_pk_mul_f32 v[80:81], v[96:97], v[80:81]
	v_pk_fma_f32 v[110:111], v[126:127], v[78:79], v[110:111]
	v_pk_fma_f32 v[112:113], v[80:81], v[128:129], v[112:113]
	s_nop 0
	v_cvt_pk_bf16_f32 v110, v110, v111
	v_cvt_pk_bf16_f32 v111, v112, v113
	global_store_dwordx2 v[26:27], v[110:111], off offset:1536
	s_cbranch_scc0 .LBB0_198
	s_mov_b32 s76, 0x8000
	s_mov_b32 s75, 0x60000

.LBB0_531:
	s_andn2_b64 vcc, exec, s[20:21]
	s_cbranch_vccnz .LBB0_528
	s_load_dwordx2 s[20:21], s[26:27], 0x0
	v_add_u32_e32 v4, s28, v3
	v_ashrrev_i32_e32 v5, 31, v4
	v_ashrrev_i32_e32 v0, 12, v4
	v_lshl_add_u64 v[6:7], v[4:5], 0, s[22:23]
	v_add_u32_e32 v0, 1, v0
	v_lshlrev_b64 v[6:7], 12, v[6:7]
	v_cndmask_b32_e64 v0, v0, 0, s[12:13]
	v_and_b32_e32 v24, 0xfc, v2
	s_waitcnt lgkmcnt(0)
	v_lshl_add_u64 v[6:7], s[20:21], 0, v[6:7]
	v_add_u32_e32 v8, s24, v0
	v_lshlrev_b32_e32 v0, 2, v24
	v_lshl_add_u64 v[2:3], v[6:7], 0, v[0:1]
	v_mov_b64_e32 v[6:7], s[34:35]
	s_movk_i32 s20, 0x6000
	v_cmp_lt_i32_e32 vcc, v199, v221
	v_mad_i64_i32 v[6:7], s[20:21], v8, s20, v[6:7]
	s_nop 0
	v_cndmask_b32_e32 v8, v220, v199, vcc
	v_cmp_lt_i32_e32 vcc, v200, v221
	v_lshlrev_b32_e32 v50, 2, v8
	v_lshlrev_b64 v[4:5], 11, v[4:5]
	v_cndmask_b32_e32 v8, v220, v200, vcc
	v_cmp_lt_i32_e32 vcc, v201, v221
	v_lshlrev_b32_e32 v51, 2, v8
	v_lshl_add_u64 v[22:23], s[72:73], 0, v[4:5]
	v_cndmask_b32_e32 v8, v220, v201, vcc
	v_cmp_lt_i32_e32 vcc, v235, v221
	v_lshlrev_b32_e32 v52, 2, v8
	v_lshl_add_u64 v[4:5], v[6:7], 0, s[8:9]
	v_cndmask_b32_e32 v8, v220, v235, vcc
	v_cmp_lt_i32_e32 vcc, v226, v221
	v_lshlrev_b32_e32 v53, 2, v8
	v_lshl_add_u64 v[18:19], v[4:5], 0, v[0:1]
	v_cndmask_b32_e32 v8, v220, v226, vcc
	v_cmp_lt_i32_e32 vcc, v227, v221
	v_lshlrev_b32_e32 v54, 2, v8
	v_lshl_add_u64 v[26:27], v[6:7], 0, v[0:1]
	v_cndmask_b32_e32 v8, v220, v227, vcc
	v_lshlrev_b32_e32 v55, 2, v8
	v_mov_b32_e32 v60, v26
	v_mov_b32_e32 v61, v27
	v_mov_b32_e32 v62, v18
	v_mov_b32_e32 v63, v19
	global_load_dwordx4 v[66:69], v[2:3], off
	global_load_dwordx4 v[70:73], v[2:3], off offset:1024
	global_load_dwordx4 v[74:77], v[2:3], off offset:2048
	global_load_dwordx4 v[78:81], v[2:3], off offset:3072
	global_load_dwordx4 v[82:85], v0, s[4:5]
	global_load_dwordx4 v[86:89], v0, s[4:5] offset:1024
	global_load_dwordx4 v[90:93], v0, s[4:5] offset:2048
	global_load_dwordx4 v[94:97], v0, s[4:5] offset:3072
	global_load_dwordx4 v[98:101], v[60:61], off
	global_load_dwordx4 v[102:105], v[60:61], off offset:1024
	global_load_dwordx4 v[106:109], v[60:61], off offset:2048
	global_load_dwordx4 v[110:113], v[60:61], off offset:3072
	global_load_dwordx4 v[114:117], v[62:63], off
	global_load_dwordx4 v[118:121], v[62:63], off offset:1024
	global_load_dwordx4 v[122:125], v[62:63], off offset:2048
	global_load_dwordx4 v[126:129], v[62:63], off offset:3072
	v_lshlrev_b32_e32 v28, 1, v24
	v_mov_b32_e32 v29, v1
	v_lshl_add_u64 v[26:27], v[22:23], 0, v[28:29]
	s_waitcnt vmcnt(12)
	v_pk_mul_f32 v[130:131], v[66:67], v[66:67]
	v_pk_fma_f32 v[130:131], v[68:69], v[68:69], v[130:131]
	v_pk_fma_f32 v[130:131], v[70:71], v[70:71], v[130:131]
	v_pk_fma_f32 v[130:131], v[72:73], v[72:73], v[130:131]
	v_pk_fma_f32 v[130:131], v[74:75], v[74:75], v[130:131]
	v_pk_fma_f32 v[130:131], v[76:77], v[76:77], v[130:131]
	v_pk_fma_f32 v[130:131], v[78:79], v[78:79], v[130:131]
	v_pk_fma_f32 v[130:131], v[80:81], v[80:81], v[130:131]
	s_nop 0
	v_add_f32_e32 v44, v130, v131
	s_nop 1
	v_add_f32_dpp v44, v44, v44 quad_perm:[1,0,3,2] row_mask:0xf bank_mask:0xf
	s_nop 1
	v_add_f32_dpp v44, v44, v44 quad_perm:[2,3,0,1] row_mask:0xf bank_mask:0xf
	s_nop 1
	v_add_f32_dpp v44, v44, v44 row_half_mirror row_mask:0xf bank_mask:0xf
	s_nop 1
	v_add_f32_dpp v44, v44, v44 row_mirror row_mask:0xf bank_mask:0xf
	v_mov_b32_e32 v45, v44
	s_nop 1
	v_permlane16_swap_b32_e32 v44, v45
	v_add_f32_e32 v44, v44, v45
	v_mov_b32_e32 v45, v44
	s_nop 1
	v_permlane32_swap_b32_e32 v44, v45
	v_add_f32_e32 v44, v44, v45
	v_fmamk_f32 v44, v44, 0x3a800000, v187
	v_cmp_gt_f32_e32 vcc, s82, v44
	v_mul_f32_e32 v45, 0x4b800000, v44
	s_nop 0
	v_cndmask_b32_e32 v44, v44, v45, vcc
	v_rsq_f32_e32 v44, v44
	s_nop 0
	v_mul_f32_e32 v45, 0x45800000, v44
	v_cndmask_b32_e32 v44, v44, v45, vcc
	s_waitcnt vmcnt(0)
	v_pk_mul_f32 v[66:67], v[66:67], v[44:45] op_sel_hi:[1,0]
	v_pk_mul_f32 v[68:69], v[68:69], v[44:45] op_sel_hi:[1,0]
	v_pk_add_f32 v[114:115], v[114:115], 1.0 op_sel_hi:[1,0]
	v_pk_add_f32 v[116:117], v[116:117], 1.0 op_sel_hi:[1,0]
	v_pk_mul_f32 v[66:67], v[82:83], v[66:67]
	v_pk_mul_f32 v[68:69], v[84:85], v[68:69]
	v_pk_fma_f32 v[98:99], v[114:115], v[66:67], v[98:99]
	v_pk_fma_f32 v[100:101], v[68:69], v[116:117], v[100:101]
	s_nop 0
	v_cvt_pk_bf16_f32 v98, v98, v99
	v_cvt_pk_bf16_f32 v99, v100, v101
	global_store_dwordx2 v[26:27], v[98:99], off
	v_pk_mul_f32 v[70:71], v[70:71], v[44:45] op_sel_hi:[1,0]
	v_pk_mul_f32 v[72:73], v[72:73], v[44:45] op_sel_hi:[1,0]
	v_pk_add_f32 v[118:119], v[118:119], 1.0 op_sel_hi:[1,0]
	v_pk_add_f32 v[120:121], v[120:121], 1.0 op_sel_hi:[1,0]
	v_pk_mul_f32 v[70:71], v[86:87], v[70:71]
	v_pk_mul_f32 v[72:73], v[88:89], v[72:73]
	v_pk_fma_f32 v[102:103], v[118:119], v[70:71], v[102:103]
	v_pk_fma_f32 v[104:105], v[72:73], v[120:121], v[104:105]
	s_nop 0
	v_cvt_pk_bf16_f32 v102, v102, v103
	v_cvt_pk_bf16_f32 v103, v104, v105
	global_store_dwordx2 v[26:27], v[102:103], off offset:512
	v_pk_mul_f32 v[74:75], v[74:75], v[44:45] op_sel_hi:[1,0]
	v_pk_mul_f32 v[76:77], v[76:77], v[44:45] op_sel_hi:[1,0]
	v_pk_add_f32 v[122:123], v[122:123], 1.0 op_sel_hi:[1,0]
	v_pk_add_f32 v[124:125], v[124:125], 1.0 op_sel_hi:[1,0]
	v_pk_mul_f32 v[74:75], v[90:91], v[74:75]
	v_pk_mul_f32 v[76:77], v[92:93], v[76:77]
	v_pk_fma_f32 v[106:107], v[122:123], v[74:75], v[106:107]
	v_pk_fma_f32 v[108:109], v[76:77], v[124:125], v[108:109]
	s_nop 0
	v_cvt_pk_bf16_f32 v106, v106, v107
	v_cvt_pk_bf16_f32 v107, v108, v109
	global_store_dwordx2 v[26:27], v[106:107], off offset:1024
	v_pk_mul_f32 v[78:79], v[78:79], v[44:45] op_sel_hi:[1,0]
	v_pk_mul_f32 v[80:81], v[80:81], v[44:45] op_sel_hi:[1,0]
	v_pk_add_f32 v[126:127], v[126:127], 1.0 op_sel_hi:[1,0]
	v_pk_add_f32 v[128:129], v[128:129], 1.0 op_sel_hi:[1,0]
	v_pk_mul_f32 v[78:79], v[94:95], v[78:79]
	v_pk_mul_f32 v[80:81], v[96:97], v[80:81]
	v_pk_fma_f32 v[110:111], v[126:127], v[78:79], v[110:111]
	v_pk_fma_f32 v[112:113], v[80:81], v[128:129], v[112:113]
	s_nop 0
	v_cvt_pk_bf16_f32 v110, v110, v111
	v_cvt_pk_bf16_f32 v111, v112, v113
	global_store_dwordx2 v[26:27], v[110:111], off offset:1536
	s_branch .LBB0_528
